# v23 + phase0->in-proj(0) grid barrier split-phase with the w_pa, w_pb, w_out weight transposes in its window (removed from phase 0)
# baseline (speedup 1.0000x reference)
; __device__ __forceinline__ unsigned xb_ld(unsigned* p)              { return __hip_atomic_load(p, __ATOMIC_RELAXED, __HIP_MEMORY_SCOPE_AGENT); }
; __device__ __forceinline__ unsigned xb_add(unsigned* p, unsigned v) { return __hip_atomic_fetch_add(p, v, __ATOMIC_RELAXED, __HIP_MEMORY_SCOPE_AGENT); }
; #define XB_SPIN(cond, bar) do { unsigned _sp = 0; while (cond) { __builtin_amdgcn_s_sleep(1); \
;     if ((++_sp & 255u) == 0u) { if (xb_ld(&(bar)[XB_TMO])) break; if (_sp > XB_SPIN_CAP) { atomicAdd(&(bar)[XB_TMO], 1u); break; } } } } while (0)
; __device__ __forceinline__ void xcd_barrier(const int wv, const XcdBarrier& b) {
;     ...
;         const unsigned old = xb_add(&bar[XB_XSUB(b.x)], 1u);
;         const unsigned gen = old / nloc;
;         if (old + 1u == (gen + 1u) * nloc) {
;             __builtin_amdgcn_fence(__ATOMIC_RELEASE, "agent");
;             asm volatile("s_waitcnt vmcnt(0)" ::: "memory");
;             const unsigned og = xb_add(&bar[XB_TOP], 1u);
;             const unsigned tg = og / nx;
;             if (og + 1u == (tg + 1u) * nx) xb_add(&bar[XB_TOPGEN], 1u);
;             else XB_SPIN(xb_ld(&bar[XB_TOPGEN]) == tg, bar);
;             __builtin_amdgcn_fence(__ATOMIC_ACQUIRE, "agent");
;             xb_add(&bar[XB_XGEN(b.x)], 1u);
;             asm volatile("s_waitcnt vmcnt(0)" ::: "memory");
;         } else {
;             XB_SPIN(xb_ld(&bar[XB_XGEN(b.x)]) == gen, bar);
.LBB0_99:
	s_lshl_b32 s0, s36, 6
	s_lshl_b32 s1, s36, 8
	s_add_u32 s25, s34, s1
	s_addc_u32 s24, s35, 0
	v_mov_b32_e32 v1, s25
	v_add_co_u32_e32 v4, vcc, 0x1000, v1
	v_mov_b32_e32 v1, s24
	s_nop 0
	v_addc_co_u32_e32 v5, vcc, 0, v1, vcc
	v_mov_b32_e32 v1, 1
	flat_atomic_add v1, v[4:5], v1 offset:1024 sc0
	v_cvt_f32_u32_e32 v3, v2
	v_sub_u32_e32 v4, 0, v2
	s_mov_b32 s1, 0
	v_rcp_iflag_f32_e32 v3, v3
	s_nop 0
	v_mul_f32_e32 v3, 0x4f7ffffe, v3
	v_cvt_u32_f32_e32 v3, v3
	v_mul_lo_u32 v4, v4, v3
	v_mul_hi_u32 v4, v3, v4
	v_add_u32_e32 v3, v3, v4
	s_waitcnt vmcnt(0) lgkmcnt(0)
	v_mul_hi_u32 v3, v1, v3
	v_mul_lo_u32 v5, v3, v2
	v_add_u32_e32 v4, 1, v1
	v_sub_u32_e32 v1, v1, v5
	v_add_u32_e32 v6, 1, v3
	v_cmp_ge_u32_e32 vcc, v1, v2
	v_sub_u32_e32 v5, v1, v2
	s_nop 0
	v_cndmask_b32_e32 v3, v3, v6, vcc
	v_cndmask_b32_e32 v1, v1, v5, vcc
	v_add_u32_e32 v5, 1, v3
	v_cmp_ge_u32_e32 vcc, v1, v2
	s_nop 1
	v_cndmask_b32_e32 v1, v3, v5, vcc
	v_mad_u64_u32 v[2:3], s[2:3], v2, v1, v[2:3]
	v_cmp_ne_u32_e32 vcc, v4, v2
	s_and_saveexec_b64 s[2:3], vcc
	s_xor_b64 s[2:3], exec, s[2:3]
	s_cbranch_execz .LBB0_112
	s_add_u32 s98, s25, 0x2400
	s_addc_u32 s99, s24, 0
	v_readfirstlane_b32 s100, v1
	s_mov_b32 s101, 0x40000

; #define LAS __attribute__((address_space(3)))
;     __device__ bool next(int i, Unit& u) const {
;         const long L = (long)i * G + c;
;         if (L < 1344) return so.next(i, u);
;         const int gi = (int)L - 1344; if (gi >= ng) return false;
;         const int gu = gstart + gi, bq = gu >> 8, wi = gu & 255;
;         u.pm = (bq - b) * 64 + (wi >> 3); u.pn = 42 + (wi & 7); return true;
;     }
; __device__ __forceinline__ void transpose_w(const int wv, LAS unsigned char* lds, const float* __restrict__ w, bf16_t* __restrict__ wt, int K, int N, const float* __restrict__ gk, int slo, int shi, float scale) {
;     const int tk = K / 64, tn = N / 64, nt = tk * tn;
;     const int t = TIDX, nl = t & 63, kg = t >> 6, n2 = t >> 3, kc = t & 7;
;     for (int tile = blockIdx.x; tile < nt; tile += gridDim.x) {
;         const int kt0 = (tile % tk) * 64, nb0 = (tile / tk) * 64;
.LBB0_129:
	s_or_b64 exec, exec, s[30:31]
	s_cmpk_gt_i32 s66, 0x53f
	s_cselect_b64 s[0:1], -1, 0
	v_writelane_b32 v253, s0, 2
	s_ashr_i32 s67, s66, 31
	s_mul_i32 s2, s55, s54
	v_writelane_b32 v253, s1, 3
	s_add_i32 s0, s66, 0xfffffac0
	v_writelane_b32 v253, s0, 4
	s_and_b32 s0, s66, 7
	s_add_i32 s0, s0, 42
	v_writelane_b32 v253, s0, 5
	s_lshr_b32 s0, s67, 29
	s_add_i32 s0, s66, s0
	s_ashr_i32 s5, s0, 3
	s_and_b32 s0, s0, -8
	s_sub_i32 s6, s66, s0
	s_cmp_gt_i32 s6, -1
	s_cselect_b64 s[0:1], -1, 0
	s_ashr_i32 s55, s54, 31
	v_writelane_b32 v253, s0, 6
	s_cmp_eq_u32 s36, 15
	s_movk_i32 s69, 0xa9
	v_writelane_b32 v253, s1, 7
	s_cselect_b64 s[0:1], -1, 0
	v_writelane_b32 v253, s0, 8
	s_cmp_eq_u32 s36, 14
	s_mul_i32 s61, s2, s33
	v_writelane_b32 v253, s1, 9
	s_cselect_b64 s[0:1], -1, 0
	v_writelane_b32 v253, s0, 10
	s_cmp_eq_u32 s36, 13
	s_movk_i32 s72, 0x2000
	v_writelane_b32 v253, s1, 11
	s_cselect_b64 s[0:1], -1, 0
	v_writelane_b32 v253, s0, 12
	s_cmp_eq_u32 s36, 12
	v_mov_b32_e32 v0, 0
	v_writelane_b32 v253, s1, 13
	s_cselect_b64 s[0:1], -1, 0
	v_writelane_b32 v253, s0, 14
	s_cmp_eq_u32 s36, 11
	s_movk_i32 s76, 0x7f
	v_writelane_b32 v253, s1, 15
	s_cselect_b64 s[0:1], -1, 0
	v_writelane_b32 v253, s0, 16
	s_cmp_eq_u32 s36, 10
	v_mov_b32_e32 v184, 1
	v_writelane_b32 v253, s1, 17
	s_cselect_b64 s[0:1], -1, 0
	v_writelane_b32 v253, s0, 18
	s_cmp_eq_u32 s36, 9
	s_movk_i32 s75, 0x3000
	v_writelane_b32 v253, s1, 19
	s_cselect_b64 s[0:1], -1, 0
	v_writelane_b32 v253, s0, 20
	s_cmp_eq_u32 s36, 8
	s_movk_i32 s33, 0x4400
	v_writelane_b32 v253, s1, 21
	s_cselect_b64 s[0:1], -1, 0
	v_writelane_b32 v253, s0, 22
	s_cmp_eq_u32 s36, 7
	v_mov_b32_e32 v185, 0x358637bd
	v_writelane_b32 v253, s1, 23
	s_cselect_b64 s[0:1], -1, 0
	v_writelane_b32 v253, s0, 24
	s_cmp_eq_u32 s36, 6
	v_mov_b32_e32 v186, 0x4f
	v_writelane_b32 v253, s1, 25
	s_cselect_b64 s[0:1], -1, 0
	v_writelane_b32 v253, s0, 26
	s_cmp_eq_u32 s36, 5
	v_mov_b32_e32 v187, 0x42800000
	v_writelane_b32 v253, s1, 27
	s_cselect_b64 s[0:1], -1, 0
	v_writelane_b32 v253, s0, 28
	s_cmp_eq_u32 s36, 4
	v_mov_b32_e32 v188, 0xff61b1e6
	v_writelane_b32 v253, s1, 29
	s_cselect_b64 s[0:1], -1, 0
	v_writelane_b32 v253, s0, 30
	s_cmp_eq_u32 s36, 3
	v_not_b32_e32 v189, 63
	v_writelane_b32 v253, s1, 31
	s_cselect_b64 s[0:1], -1, 0
	v_writelane_b32 v253, s0, 32
	s_cmp_eq_u32 s36, 2
	v_mov_b32_e32 v190, 0x42000000
	v_writelane_b32 v253, s1, 33
	s_cselect_b64 s[0:1], -1, 0
	v_writelane_b32 v253, s0, 34
	s_cmp_eq_u32 s36, 1
	s_mov_b32 s37, 0xfe967699
	v_writelane_b32 v253, s1, 35
	s_cselect_b64 s[0:1], -1, 0
	v_writelane_b32 v253, s0, 36
	s_cmp_eq_u32 s36, 0
	s_mov_b32 s36, 0x800000
	v_writelane_b32 v253, s1, 37
	s_cselect_b64 s[0:1], -1, 0
	v_writelane_b32 v253, s0, 38
	s_cmpk_lt_i32 s66, 0x300
	s_movk_i32 s92, 0xc00
	v_writelane_b32 v253, s1, 39
	s_cselect_b64 s[0:1], -1, 0
	v_writelane_b32 v253, s0, 40
	s_movk_i32 s38, 0x210
	s_mov_b32 s78, 0x80000
	v_writelane_b32 v253, s1, 41
	s_and_b32 s0, s66, 63
	s_and_b32 s1, s66, 0xffffff00
	s_cmpk_eq_i32 s1, 0x100
	s_cselect_b32 s1, 2, 4
	s_cmpk_gt_u32 s66, 0xff
	s_cselect_b32 s60, s1, 0
	s_lshr_b32 s1, 64, s60
	s_xor_b32 s3, s60, 6
	s_add_i32 s1, s1, -1
	s_lshr_b32 s62, s0, s3
	s_and_b32 s0, s1, s0
	s_lshl_b32 s0, s0, 7
	v_writelane_b32 v253, s0, 42
	s_lshl_b32 s0, s66, 1
	s_and_b32 s64, s0, 0xffffff80
	s_ashr_i32 s65, s64, 31
	s_lshl_b32 s63, s66, 9
	s_lshl_b32 s68, s54, 9
	s_cmpk_lt_i32 s66, 0x100
	s_cselect_b64 s[0:1], -1, 0
	v_writelane_b32 v253, s0, 43
	s_mov_b32 s79, 0
	s_mov_b32 s83, 0
	v_writelane_b32 v253, s1, 44
	s_lshl_b32 s0, s66, 2
	s_and_b32 s0, s0, 0xffffff00
	s_lshl_b32 s1, s66, 7
	s_and_b32 s3, s1, 0x1f80
	s_ashr_i32 s1, s0, 31
	s_cmp_lt_i32 s6, 0
	s_cselect_b32 s2, s69, 0xa8
	s_mul_i32 s2, s6, s2
	s_add_i32 s2, s2, s5
	s_mul_i32 s4, s3, 0x2200
	v_writelane_b32 v253, s6, 45
	s_mul_hi_i32 s3, s2, 0x30c30c31
	v_writelane_b32 v253, s5, 46
	s_lshr_b32 s5, s3, 31
	s_ashr_i32 s3, s3, 6
	s_add_i32 s3, s3, s5
	s_lshl_b32 s5, s3, 3
	s_mulk_i32 s3, 0x150
	s_sub_i32 s2, s2, s3
	s_bfe_u32 s3, s2, 0x3001c
	s_add_i32 s3, s2, s3
	s_sext_i32_i16 s6, s3
	s_and_b32 s3, s3, 0xfff8
	s_sub_i32 s2, s2, s3
	s_sext_i32_i16 s2, s2
	s_add_i32 s2, s5, s2
	v_writelane_b32 v253, s2, 47
	s_ashr_i32 s2, s6, 3
	s_add_i32 s5, s66, s54
	v_writelane_b32 v253, s2, 48
	s_lshl_b32 s2, s5, 1
	v_writelane_b32 v253, s2, 49
	s_lshl_b32 s2, s54, 1
	v_writelane_b32 v253, s2, 50
	s_lshl_b32 s2, s66, 11
	v_writelane_b32 v253, s2, 51
	s_lshl_b32 s70, s54, 11
	s_lshl_b64 s[2:3], s[66:67], 18
	s_add_u32 s2, s2, 0x4c00000
	v_writelane_b32 v253, s2, 52
	s_addc_u32 s2, s3, 0
	v_writelane_b32 v253, s2, 53
	s_lshl_b32 s2, s5, 2
	v_writelane_b32 v253, s2, 54
	s_lshl_b32 s2, s54, 2
	v_writelane_b32 v253, s2, 55
	s_lshl_b32 s2, s5, 7
	v_writelane_b32 v253, s2, 56
	s_lshl_b32 s2, s54, 7
	v_writelane_b32 v253, s2, 57
	s_lshl_b32 s2, s66, 12
	v_writelane_b32 v253, s2, 58
	s_lshl_b32 s2, s4, 1
	v_writelane_b32 v253, s2, 59
	s_lshl_b64 s[0:1], s[0:1], 1
	v_writelane_b32 v254, s66, 0
	v_writelane_b32 v253, s0, 60
	s_lshl_b32 s31, s54, 10
	v_writelane_b32 v254, s67, 1
	s_lshl_b32 s71, s54, 14
	v_writelane_b32 v253, s1, 61
	s_lshl_b64 s[0:1], s[54:55], 18
	v_writelane_b32 v254, s54, 2
	s_add_i32 s73, 0, 0x21ff0
	s_add_i32 s74, 0, 0x21ff4
	v_writelane_b32 v254, s55, 3
	v_writelane_b32 v254, s56, 4
	s_add_i32 s77, 0, 0x10800
	v_writelane_b32 v253, s0, 62
	v_writelane_b32 v254, s57, 5
	v_writelane_b32 v254, s53, 6
	v_writelane_b32 v254, s58, 7
	v_writelane_b32 v253, s1, 63
	s_mov_b64 s[88:89], 0x80
	v_writelane_b32 v254, s59, 8
	v_writelane_b32 v254, s61, 9
	v_writelane_b32 v254, s60, 10
	v_writelane_b32 v254, s62, 11
	v_writelane_b32 v254, s64, 12
	s_waitcnt lgkmcnt(0)
	s_barrier
	v_writelane_b32 v254, s65, 13
	v_writelane_b32 v254, s63, 14
	v_writelane_b32 v254, s68, 15
	v_writelane_b32 v254, s70, 16
	v_writelane_b32 v254, s71, 17
	v_writelane_b32 v254, s73, 18
	v_writelane_b32 v254, s74, 19
	v_writelane_b32 v254, s77, 20
	v_writelane_b32 v254, s31, 21
	s_mov_b64 s[2:3], s[56:57]
	s_load_dwordx2 s[10:11], s[56:57], 0x70
	s_waitcnt lgkmcnt(0)
	v_mbcnt_lo_u32_b32 v2, -1, 0
	v_mbcnt_hi_u32_b32 v2, -1, v2
	s_load_dwordx2 s[0:1], s[2:3], 0x40
	v_add_u32_e32 v3, s53, v2
	v_ashrrev_i32_e32 v5, 3, v3
	v_ashrrev_i32_e32 v3, 6, v3
	s_movk_i32 s6, 0x90
	v_and_b32_e32 v4, 63, v2
	v_and_b32_e32 v2, 7, v2
	v_lshlrev_b32_e32 v6, 3, v3
	v_lshlrev_b32_e32 v8, 4, v3
	v_mul_lo_u32 v3, v5, s6
	s_waitcnt lgkmcnt(0)
	s_add_u32 s4, s10, 0x1a00000
	v_mad_u32_u24 v7, v4, s6, 0
	v_add_u32_e32 v9, 0, v3
	v_lshlrev_b32_e32 v10, 4, v2
	v_lshlrev_b32_e32 v2, 3, v2
	s_addc_u32 s5, s11, 0
	v_mov_b32_e32 v3, 0
	s_lshl_b32 s12, s66, 6
	s_lshl_b32 s13, s54, 6
	v_add_u32_e32 v7, v7, v8
	v_add_u32_e32 v8, v9, v10
	v_lshlrev_b32_e32 v2, 1, v2
	s_mov_b32 s14, s66
; #define LAS __attribute__((address_space(3)))
; __device__ __forceinline__ unsigned cvt_pk_bf16(float lo, float hi) { unsigned r; asm volatile("v_cvt_pk_bf16_f32 %0, %1, %2" : "=v"(r) : "v"(lo), "v"(hi)); return r; }
; __device__ __forceinline__ void transpose_w(const int wv, LAS unsigned char* lds, const float* __restrict__ w, bf16_t* __restrict__ wt, int K, int N, const float* __restrict__ gk, int slo, int shi, float scale) {
;     const int tk = K / 64, tn = N / 64, nt = tk * tn;
;     const int t = TIDX, nl = t & 63, kg = t >> 6, n2 = t >> 3, kc = t & 7;
;     for (int tile = blockIdx.x; tile < nt; tile += gridDim.x) {
;         const int kt0 = (tile % tk) * 64, nb0 = (tile / tk) * 64;
;         const int k0 = kt0 + kg * 8, n = nb0 + nl;
;         float v[8];
; #pragma unroll
;         for (int j = 0; j < 8; ++j) { float g = gk ? gk[k0 + j] : 1.0f; v[j] = w[(size_t)(k0 + j) * N + n] * g; }
;         if (n >= slo && n < shi) {
; #pragma unroll
;             for (int j = 0; j < 8; ++j) v[j] *= scale;
;         }
;         u32x4 o; o.x = cvt_pk_bf16(v[0], v[1]); o.y = cvt_pk_bf16(v[2], v[3]); o.z = cvt_pk_bf16(v[4], v[5]); o.w = cvt_pk_bf16(v[6], v[7]);
;         *(LAS u32x4*)(lds + nl * 144 + kg * 16) = o;
;         __syncthreads();
;         *(u32x4*)(wt + (size_t)(nb0 + n2) * K + kt0 + kc * 8) = *(const LAS u32x4*)(lds + n2 * 144 + kc * 16);
;         __syncthreads();
;     }
; }
.Lwb_29:
	s_ashr_i32 s6, s14, 31
	s_lshr_b32 s6, s6, 27
	s_add_i32 s6, s14, s6
	s_ashr_i32 s6, s6, 5
	s_lshl_b32 s7, s6, 11
	s_lshl_b32 s15, s6, 6
	s_sub_i32 s6, s12, s7
	v_or_b32_e32 v10, s15, v4
	v_add_u32_e32 v12, s6, v6
	v_ashrrev_i32_e32 v11, 31, v10
	v_ashrrev_i32_e32 v13, 31, v12
	v_add_u32_e32 v14, 1, v12
	v_add_u32_e32 v16, 2, v12
	v_add_u32_e32 v18, 3, v12
	v_add_u32_e32 v20, 4, v12
	v_add_u32_e32 v22, 5, v12
	v_add_u32_e32 v24, 6, v12
	v_add_u32_e32 v26, 7, v12
	v_lshl_add_u64 v[10:11], v[10:11], 2, s[0:1]
	v_lshlrev_b64 v[12:13], 12, v[12:13]
	v_ashrrev_i32_e32 v15, 31, v14
	v_ashrrev_i32_e32 v17, 31, v16
	v_ashrrev_i32_e32 v19, 31, v18
	v_ashrrev_i32_e32 v21, 31, v20
	v_ashrrev_i32_e32 v23, 31, v22
	v_ashrrev_i32_e32 v25, 31, v24
	v_ashrrev_i32_e32 v27, 31, v26
	v_lshl_add_u64 v[12:13], v[10:11], 0, v[12:13]
	v_lshlrev_b64 v[14:15], 12, v[14:15]
	v_lshlrev_b64 v[16:17], 12, v[16:17]
	v_lshlrev_b64 v[18:19], 12, v[18:19]
	v_lshlrev_b64 v[20:21], 12, v[20:21]
	v_lshlrev_b64 v[22:23], 12, v[22:23]
	v_lshlrev_b64 v[24:25], 12, v[24:25]
	v_lshlrev_b64 v[26:27], 12, v[26:27]
	v_lshl_add_u64 v[14:15], v[10:11], 0, v[14:15]
	v_lshl_add_u64 v[16:17], v[10:11], 0, v[16:17]
	v_lshl_add_u64 v[18:19], v[10:11], 0, v[18:19]
	v_lshl_add_u64 v[20:21], v[10:11], 0, v[20:21]
	v_lshl_add_u64 v[22:23], v[10:11], 0, v[22:23]
	v_lshl_add_u64 v[24:25], v[10:11], 0, v[24:25]
	v_lshl_add_u64 v[10:11], v[10:11], 0, v[26:27]
	global_load_dword v9, v[12:13], off nt
	global_load_dword v26, v[14:15], off nt
	global_load_dword v27, v[18:19], off nt
	global_load_dword v28, v[24:25], off nt
	global_load_dword v29, v[20:21], off nt
	global_load_dword v30, v[16:17], off nt
	global_load_dword v31, v[22:23], off nt
	global_load_dword v32, v[10:11], off nt
	v_add_u32_e32 v10, s15, v5
	v_ashrrev_i32_e32 v11, 31, v10
	v_lshlrev_b64 v[10:11], 12, v[10:11]
	s_ashr_i32 s7, s6, 31
	v_lshl_add_u64 v[10:11], s[4:5], 0, v[10:11]
	v_lshl_add_u64 v[14:15], s[6:7], 1, v[10:11]
	s_add_i32 s14, s14, s54
	s_add_i32 s12, s12, s13
	s_cmpk_lt_i32 s14, 0x200
	v_lshl_add_u64 v[14:15], v[14:15], 0, v[2:3]
	s_waitcnt vmcnt(6)
	v_cvt_pk_bf16_f32 v10, v9, v26
	s_waitcnt vmcnt(2)
	v_cvt_pk_bf16_f32 v11, v30, v27
	s_waitcnt vmcnt(1)
	v_cvt_pk_bf16_f32 v12, v29, v31
	s_waitcnt vmcnt(0)
	v_cvt_pk_bf16_f32 v13, v28, v32
	ds_write_b128 v7, v[10:13]
	s_waitcnt lgkmcnt(0)
	s_barrier
	ds_read_b128 v[10:13], v8
	s_waitcnt lgkmcnt(0)
	global_store_dwordx4 v[14:15], v[10:13], off
	s_barrier
	s_cbranch_scc1 .Lwb_29
	s_cmpk_gt_i32 s66, 0x7f
	v_mbcnt_lo_u32_b32 v2, -1, 0
	v_mbcnt_hi_u32_b32 v2, -1, v2
	s_cbranch_scc1 .Lwa_end
	s_load_dwordx2 s[0:1], s[2:3], 0x38
	v_add_u32_e32 v3, s53, v2
	v_ashrrev_i32_e32 v5, 3, v3
	v_ashrrev_i32_e32 v3, 6, v3
	s_movk_i32 s6, 0x90
	v_and_b32_e32 v4, 63, v2
	v_and_b32_e32 v2, 7, v2
	v_lshlrev_b32_e32 v6, 3, v3
	v_lshlrev_b32_e32 v8, 4, v3
	v_mul_lo_u32 v3, v5, s6
	s_waitcnt lgkmcnt(0)
	s_add_u32 s4, s10, 0x1900000
	v_mad_u32_u24 v7, v4, s6, 0
	v_add_u32_e32 v9, 0, v3
	v_lshlrev_b32_e32 v10, 4, v2
	v_lshlrev_b32_e32 v2, 3, v2
	s_addc_u32 s5, s11, 0
	v_mov_b32_e32 v3, 0
	s_lshl_b32 s12, s66, 6
	s_lshl_b32 s13, s54, 6
	v_add_u32_e32 v7, v7, v8
	v_add_u32_e32 v8, v9, v10
	v_lshlrev_b32_e32 v2, 1, v2
	s_mov_b32 s14, s66

; __device__ __forceinline__ void xcd_barrier(const int wv, const XcdBarrier& b) {
;     ...
;     __syncthreads();
; }
.Lgwp0_done:
	s_barrier
	s_branch .LBB0_132
